# w_ffn_down conversion moved from phase 0 into the idle half of INPROJ last tile round (workgroups bx>=G/2), on top of POST rewrite + lora writer + scan loop
# speedup vs baseline: 1.0013x; 1.0013x over previous
.LBB0_21:
	v_readlane_b32 s0, v254, 24
	v_readlane_b32 s12, v253, 0
	s_sub_u32 s1, s0, 1
	s_mul_hi_u32 s2, s1, 0x38e38e39
	s_lshr_b32 s2, s2, 1
	s_mul_i32 s3, s2, 9
	s_cmp_eq_u32 s3, s1
	s_cbranch_scc0 .Lcd_skip
	s_cmp_lt_u32 s2, 4
	s_cbranch_scc0 .Lcd_skip
	s_lshr_b32 s13, s80, 1
	s_cmp_ge_u32 s12, s13
	s_cbranch_scc0 .Lcd_skip
	s_load_dwordx2 s[18:19], s[28:29], 0xc0
	s_load_dwordx2 s[20:21], s[28:29], 0xf0
	v_and_b32_e32 v1, 31, v197
	v_lshrrev_b32_e32 v2, 5, v197
	v_lshlrev_b32_e32 v3, 13, v2
	v_lshl_add_u32 v3, v1, 2, v3
	v_readfirstlane_b32 s14, v160
	v_mul_u32_u24_e32 v4, 33, v2
	v_add_lshl_u32 v4, v4, v1, 2
	v_and_b32_e32 v5, 7, v197
	v_lshrrev_b32_e32 v6, 3, v197
	v_mul_u32_u24_e32 v7, 0x108, v5
	v_add_lshl_u32 v7, v7, v6, 2
	v_lshlrev_b32_e32 v8, 13, v6
	v_lshl_add_u32 v8, v5, 3, v8
	v_lshlrev_b32_e32 v8, 1, v8
	s_lshr_b32 s14, s14, 6
	s_mul_i32 s15, s14, 0x2100
	v_add_u32_e32 v4, s15, v4
	v_add_u32_e32 v7, s15, v7
	s_sub_u32 s15, s12, s13
	s_lshl_b32 s15, s15, 3
	s_add_u32 s14, s15, s14
	s_sub_u32 s15, s80, s13
	s_lshl_b32 s15, s15, 3
	s_waitcnt lgkmcnt(0)
	s_lshl_b32 s3, s2, 26
	s_add_u32 s18, s18, s3
	s_addc_u32 s19, s19, 0
	s_lshl_b32 s3, s2, 25
	s_add_u32 s20, s20, s3
	s_addc_u32 s21, s21, 0
	s_add_u32 s20, s20, 0xe900000
	s_addc_u32 s21, s21, 0
.Lcd_loop:
	s_cmp_lt_u32 s14, 0x2000
	s_cbranch_scc0 .Lcd_done
	s_lshr_b32 s0, s14, 6
	s_and_b32 s1, s14, 63
	s_lshl_b32 s3, s0, 19
	s_lshl_b32 s13, s1, 7
	s_add_u32 s3, s3, s13
	s_add_u32 s22, s18, s3
	s_addc_u32 s23, s19, 0
	global_load_dword v32, v3, s[22:23]
	s_add_u32 s22, s22, 0x4000
	s_addc_u32 s23, s23, 0
	global_load_dword v33, v3, s[22:23]
	s_add_u32 s22, s22, 0x4000
	s_addc_u32 s23, s23, 0
	global_load_dword v34, v3, s[22:23]
	s_add_u32 s22, s22, 0x4000
	s_addc_u32 s23, s23, 0
	global_load_dword v35, v3, s[22:23]
	s_add_u32 s22, s22, 0x4000
	s_addc_u32 s23, s23, 0
	global_load_dword v36, v3, s[22:23]
	s_add_u32 s22, s22, 0x4000
	s_addc_u32 s23, s23, 0
	global_load_dword v37, v3, s[22:23]
	s_add_u32 s22, s22, 0x4000
	s_addc_u32 s23, s23, 0
	global_load_dword v38, v3, s[22:23]
	s_add_u32 s22, s22, 0x4000
	s_addc_u32 s23, s23, 0
	global_load_dword v39, v3, s[22:23]
	s_add_u32 s22, s22, 0x4000
	s_addc_u32 s23, s23, 0
	global_load_dword v40, v3, s[22:23]
	s_add_u32 s22, s22, 0x4000
	s_addc_u32 s23, s23, 0
	global_load_dword v41, v3, s[22:23]
	s_add_u32 s22, s22, 0x4000
	s_addc_u32 s23, s23, 0
	global_load_dword v42, v3, s[22:23]
	s_add_u32 s22, s22, 0x4000
	s_addc_u32 s23, s23, 0
	global_load_dword v43, v3, s[22:23]
	s_add_u32 s22, s22, 0x4000
	s_addc_u32 s23, s23, 0
	global_load_dword v44, v3, s[22:23]
	s_add_u32 s22, s22, 0x4000
	s_addc_u32 s23, s23, 0
	global_load_dword v45, v3, s[22:23]
	s_add_u32 s22, s22, 0x4000
	s_addc_u32 s23, s23, 0
	global_load_dword v46, v3, s[22:23]
	s_add_u32 s22, s22, 0x4000
	s_addc_u32 s23, s23, 0
	global_load_dword v47, v3, s[22:23]
	s_add_u32 s22, s22, 0x4000
	s_addc_u32 s23, s23, 0
	global_load_dword v48, v3, s[22:23]
	s_add_u32 s22, s22, 0x4000
	s_addc_u32 s23, s23, 0
	global_load_dword v49, v3, s[22:23]
	s_add_u32 s22, s22, 0x4000
	s_addc_u32 s23, s23, 0
	global_load_dword v50, v3, s[22:23]
	s_add_u32 s22, s22, 0x4000
	s_addc_u32 s23, s23, 0
	global_load_dword v51, v3, s[22:23]
	s_add_u32 s22, s22, 0x4000
	s_addc_u32 s23, s23, 0
	global_load_dword v52, v3, s[22:23]
	s_add_u32 s22, s22, 0x4000
	s_addc_u32 s23, s23, 0
	global_load_dword v53, v3, s[22:23]
	s_add_u32 s22, s22, 0x4000
	s_addc_u32 s23, s23, 0
	global_load_dword v54, v3, s[22:23]
	s_add_u32 s22, s22, 0x4000
	s_addc_u32 s23, s23, 0
	global_load_dword v55, v3, s[22:23]
	s_add_u32 s22, s22, 0x4000
	s_addc_u32 s23, s23, 0
	global_load_dword v56, v3, s[22:23]
	s_add_u32 s22, s22, 0x4000
	s_addc_u32 s23, s23, 0
	global_load_dword v57, v3, s[22:23]
	s_add_u32 s22, s22, 0x4000
	s_addc_u32 s23, s23, 0
	global_load_dword v58, v3, s[22:23]
	s_add_u32 s22, s22, 0x4000
	s_addc_u32 s23, s23, 0
	global_load_dword v59, v3, s[22:23]
	s_add_u32 s22, s22, 0x4000
	s_addc_u32 s23, s23, 0
	global_load_dword v60, v3, s[22:23]
	s_add_u32 s22, s22, 0x4000
	s_addc_u32 s23, s23, 0
	global_load_dword v61, v3, s[22:23]
	s_add_u32 s22, s22, 0x4000
	s_addc_u32 s23, s23, 0
	global_load_dword v62, v3, s[22:23]
	s_add_u32 s22, s22, 0x4000
	s_addc_u32 s23, s23, 0
	global_load_dword v63, v3, s[22:23]
	s_lshl_b32 s3, s1, 19
	s_lshl_b32 s13, s0, 7
	s_add_u32 s3, s3, s13
	s_add_u32 s22, s20, s3
	s_addc_u32 s23, s21, 0
	s_waitcnt vmcnt(0)
	ds_write_b32 v4, v32 offset:0
	ds_write_b32 v4, v33 offset:264
	ds_write_b32 v4, v34 offset:528
	ds_write_b32 v4, v35 offset:792
	ds_write_b32 v4, v36 offset:1056
	ds_write_b32 v4, v37 offset:1320
	ds_write_b32 v4, v38 offset:1584
	ds_write_b32 v4, v39 offset:1848
	ds_write_b32 v4, v40 offset:2112
	ds_write_b32 v4, v41 offset:2376
	ds_write_b32 v4, v42 offset:2640
	ds_write_b32 v4, v43 offset:2904
	ds_write_b32 v4, v44 offset:3168
	ds_write_b32 v4, v45 offset:3432
	ds_write_b32 v4, v46 offset:3696
	ds_write_b32 v4, v47 offset:3960
	ds_write_b32 v4, v48 offset:4224
	ds_write_b32 v4, v49 offset:4488
	ds_write_b32 v4, v50 offset:4752
	ds_write_b32 v4, v51 offset:5016
	ds_write_b32 v4, v52 offset:5280
	ds_write_b32 v4, v53 offset:5544
	ds_write_b32 v4, v54 offset:5808
	ds_write_b32 v4, v55 offset:6072
	ds_write_b32 v4, v56 offset:6336
	ds_write_b32 v4, v57 offset:6600
	ds_write_b32 v4, v58 offset:6864
	ds_write_b32 v4, v59 offset:7128
	ds_write_b32 v4, v60 offset:7392
	ds_write_b32 v4, v61 offset:7656
	ds_write_b32 v4, v62 offset:7920
	ds_write_b32 v4, v63 offset:8184
	s_waitcnt lgkmcnt(0)
	ds_read2_b32 v[64:65], v7 offset0:0 offset1:33
	ds_read2_b32 v[66:67], v7 offset0:66 offset1:99
	ds_read2_b32 v[68:69], v7 offset0:132 offset1:165
	ds_read2_b32 v[70:71], v7 offset0:198 offset1:231
	s_waitcnt lgkmcnt(0)
	v_cvt_pk_bf16_f32 v72, v64, v65
	v_cvt_pk_bf16_f32 v73, v66, v67
	v_cvt_pk_bf16_f32 v74, v68, v69
	v_cvt_pk_bf16_f32 v75, v70, v71
	global_store_dwordx4 v8, v[72:75], s[22:23]
	s_add_u32 s22, s22, 0x20000
	s_addc_u32 s23, s23, 0
	ds_read2_b32 v[64:65], v7 offset0:8 offset1:41
	ds_read2_b32 v[66:67], v7 offset0:74 offset1:107
	ds_read2_b32 v[68:69], v7 offset0:140 offset1:173
	ds_read2_b32 v[70:71], v7 offset0:206 offset1:239
	s_waitcnt lgkmcnt(0)
	v_cvt_pk_bf16_f32 v76, v64, v65
	v_cvt_pk_bf16_f32 v77, v66, v67
	v_cvt_pk_bf16_f32 v78, v68, v69
	v_cvt_pk_bf16_f32 v79, v70, v71
	global_store_dwordx4 v8, v[76:79], s[22:23]
	s_add_u32 s22, s22, 0x20000
	s_addc_u32 s23, s23, 0
	ds_read2_b32 v[64:65], v7 offset0:16 offset1:49
	ds_read2_b32 v[66:67], v7 offset0:82 offset1:115
	ds_read2_b32 v[68:69], v7 offset0:148 offset1:181
	ds_read2_b32 v[70:71], v7 offset0:214 offset1:247
	s_waitcnt lgkmcnt(0)
	v_cvt_pk_bf16_f32 v80, v64, v65
	v_cvt_pk_bf16_f32 v81, v66, v67
	v_cvt_pk_bf16_f32 v82, v68, v69
	v_cvt_pk_bf16_f32 v83, v70, v71
	global_store_dwordx4 v8, v[80:83], s[22:23]
	s_add_u32 s22, s22, 0x20000
	s_addc_u32 s23, s23, 0
	ds_read2_b32 v[64:65], v7 offset0:24 offset1:57
	ds_read2_b32 v[66:67], v7 offset0:90 offset1:123
	ds_read2_b32 v[68:69], v7 offset0:156 offset1:189
	ds_read2_b32 v[70:71], v7 offset0:222 offset1:255
	s_waitcnt lgkmcnt(0)
	v_cvt_pk_bf16_f32 v84, v64, v65
	v_cvt_pk_bf16_f32 v85, v66, v67
	v_cvt_pk_bf16_f32 v86, v68, v69
	v_cvt_pk_bf16_f32 v87, v70, v71
	global_store_dwordx4 v8, v[84:87], s[22:23]
	s_add_u32 s14, s14, s15
	s_branch .Lcd_loop
.Lcd_done:
	s_waitcnt vmcnt(0)
.Lcd_skip:
	s_nop 0
	v_writelane_b32 v255, s46, 23
	v_readlane_b32 s0, v253, 48
	s_add_i32 s0, s0, 1
	v_writelane_b32 v255, s47, 24
	v_writelane_b32 v255, s48, 18
	v_writelane_b32 v253, s0, 48
	v_writelane_b32 v255, s49, 19
	v_readlane_b32 s77, v254, 24
	v_readlane_b32 s0, v253, 49
	v_readlane_b32 s12, v254, 3
	v_writelane_b32 v255, s54, 20
	s_add_i32 s77, s77, 1
	s_add_i32 s0, s0, 1
	v_readlane_b32 s13, v254, 4
	v_writelane_b32 v255, s24, 21
	v_readlane_b32 s14, v254, 1
	v_readlane_b32 s18, v254, 6
	v_readlane_b32 s20, v254, 8
	v_readlane_b32 s22, v254, 10
	v_readlane_b32 s24, v254, 12
	s_mov_b32 s70, 0xfffe0000
	v_writelane_b32 v253, s0, 49
	s_cmp_ge_i32 s77, s13
	v_writelane_b32 v255, s16, 22
	v_readlane_b32 s15, v254, 2
	v_readlane_b32 s16, v254, 5
	v_readlane_b32 s19, v254, 7
	v_readlane_b32 s21, v254, 9
	v_readlane_b32 s23, v254, 11
	v_readlane_b32 s25, v254, 13
	v_readlane_b32 s33, v254, 14
	v_readlane_b32 s68, v254, 15
	s_movk_i32 s71, 0x3ff
	s_movk_i32 s69, 0x2000
	s_movk_i32 s72, 0x7ff
	s_movk_i32 s73, 0x1fff
	s_movk_i32 s74, 0x1000
	s_movk_i32 s75, 0x2400
	s_mov_b32 s76, 0xf800000
	s_cbranch_scc1 .LBB0_529

.LBB0_110:
	s_or_b64 exec, exec, s[54:55]
	s_branch .LBB0_112
	s_load_dwordx2 s[18:19], s[28:29], 0xc0
	s_lshl_b64 s[26:27], s[52:53], 2
	v_lshl_add_u64 v[0:1], s[52:53], 1, v[22:23]
	s_mov_b64 s[52:53], 0
	v_mov_b32_e32 v42, v10
	s_waitcnt lgkmcnt(0)
	s_add_u32 s18, s18, s26
	s_addc_u32 s19, s19, s27
	v_lshl_add_u64 v[2:3], s[18:19], 0, v[156:157]
